# hyena pair transform: input stage performs the first forward pass(es) in registers before the data goes to LDS; wave-local passes run without block barriers
# speedup vs baseline: 1.1497x; 1.0057x over previous
; DI float cos2pi(float x) { return __builtin_amdgcn_cosf(x); }
; DI float sin2pi(float x) { return __builtin_amdgcn_sinf(x); }
; template <bool INV>
; DI void fft_lds(float2* buf_, int L, int logL, int gtid, int NTG) {
;     ...
;     for (; s >= 2; s >>= 2) {
;       const int S = s >> 1;
;       const float i4 = 0.25f / (float)S;
; #pragma unroll 8
;       for (int t = gtid; t < (L >> 2); t += NTG) {
;         const int k = t & (S - 1), base = ((t - k) << 2) | k;
;         const v2f a0 = buf[base], a1 = buf[base + S], a2 = buf[base + 2 * S], a3 = buf[base + 3 * S];
;         const float fr = (float)k * i4;
;         const v2f w1 = v2f{cos2pi(fr), sin2pi(fr)};
;         const v2f w2 = vcmul(w1, w1);
;         const v2f x0 = a0 + a2;
;         const v2f x2 = vcmulc(a0 - a2, w1);
;         const v2f x1 = a1 + a3;
;         const v2f d13 = vcmulc(a1 - a3, w1);
;         const v2f x3 = v2f{d13.y, -d13.x};
;         buf[base] = x0 + x1;
;         buf[base + S] = vcmulc(x0 - x1, w2);
;         buf[base + 2 * S] = x2 + x3;
;         buf[base + 3 * S] = vcmulc(x2 - x3, w2);
;       }
;       __syncthreads();
;     }
.Lffs_pg_nb:
	s_or_b64 exec, exec, s[24:25]
	s_lshr_b32 s6, s6, 2
	s_waitcnt lgkmcnt(0)
	s_branch .LBB0_610

; DI float bf2f(bf16 b) { return __uint_as_float(((unsigned)b) << 16); }
; DI float cos2pi(float x) { return __builtin_amdgcn_cosf(x); }
; DI float sin2pi(float x) { return __builtin_amdgcn_sinf(x); }
; template <bool INV>
; DI void fft_lds(float2* buf_, int L, int logL, int gtid, int NTG) {
;     ...
;       for (int t = gtid; t < (L >> 2); t += NTG) {
;         const int k = t & (S - 1), base = ((t - k) << 2) | k;
;         const v2f a0 = buf[base], a1 = buf[base + S], a2 = buf[base + 2 * S], a3 = buf[base + 3 * S];
;         const float fr = (float)k * i4;
;         const v2f w1 = v2f{cos2pi(fr), sin2pi(fr)};
;         const v2f w2 = vcmul(w1, w1);
;         const v2f x0 = a0 + a2;
;         const v2f x2 = vcmulc(a0 - a2, w1);
;         const v2f x1 = a1 + a3;
;         const v2f d13 = vcmulc(a1 - a3, w1);
;         const v2f x3 = v2f{d13.y, -d13.x};
;         buf[base] = x0 + x1;
;         buf[base + S] = vcmulc(x0 - x1, w2);
;         buf[base + 2 * S] = x2 + x3;
;         buf[base + 3 * S] = vcmulc(x2 - x3, w2);
;       }
; DI void hyena_item(const Ctx& c, int ch, float* red) {
;     ...
;       for (int p = 0; p < 2; ++p) {
; #pragma unroll 4
;         for (int n = gtid; n < L; n += NTG) {
;           const float a = bf2f(zin[r0 + n]), b = bf2f(zin[r1 + n]);
;           if (p == 0) bufg[n] = make_float2(a, b);
;           else {
;             const float fr = (float)n * i2L; const float cs = cos2pi(fr), sn = sin2pi(fr);
;             bufg[n] = make_float2(a * cs + b * sn, b * cs - a * sn);
;           }
;         }
.LBB0_666:
	s_xor_b64 s[42:43], s[0:1], -1
	v_readfirstlane_b32 s0, v12
	v_readfirstlane_b32 s1, v13
	v_readfirstlane_b32 s4, v16
	v_readfirstlane_b32 s5, v17
	v_lshlrev_b32_e32 v246, 1, v38
	v_lshl_add_u32 v247, v38, 3, v40
	v_mov_b32_e32 v250, v38
	s_mov_b32 s100, 0
	s_cmp_eq_u32 s61, 64
	s_cbranch_scc1 .Lhz2_g0
	v_add_u32_e32 v248, 0x10000, v247
.Lhz2_l1:
	v_add_u32_e32 v251, 0x2000, v246
	v_add_u32_e32 v252, 0x4000, v246
	v_add_u32_e32 v253, 0x6000, v246
	global_load_ushort v230, v246, s[0:1]
	global_load_ushort v234, v246, s[4:5]
	global_load_ushort v238, v246, s[0:1] offset:1024
	global_load_ushort v242, v246, s[4:5] offset:1024
	global_load_ushort v231, v251, s[0:1]
	global_load_ushort v235, v251, s[4:5]
	global_load_ushort v239, v251, s[0:1] offset:1024
	global_load_ushort v243, v251, s[4:5] offset:1024
	global_load_ushort v232, v252, s[0:1]
	global_load_ushort v236, v252, s[4:5]
	global_load_ushort v240, v252, s[0:1] offset:1024
	global_load_ushort v244, v252, s[4:5] offset:1024
	global_load_ushort v233, v253, s[0:1]
	global_load_ushort v237, v253, s[4:5]
	global_load_ushort v241, v253, s[0:1] offset:1024
	global_load_ushort v245, v253, s[4:5] offset:1024
	v_cvt_f32_u32_e32 v112, v250
	v_mul_f32_e32 v112, 0x38800000, v112
	v_cos_f32_e32 v106, v112
	v_sin_f32_e32 v107, v112
	s_nop 0
	v_mul_f32_e32 v108, v107, v107
	v_mul_f32_e32 v109, v107, v106
	v_fma_f32 v108, v106, v106, -v108
	v_fma_f32 v109, v106, v107, v109
	s_waitcnt vmcnt(0)
	v_lshlrev_b32_e32 v230, 16, v230
	v_lshlrev_b32_e32 v234, 16, v234
	v_lshlrev_b32_e32 v231, 16, v231
	v_lshlrev_b32_e32 v235, 16, v235
	v_lshlrev_b32_e32 v232, 16, v232
	v_lshlrev_b32_e32 v236, 16, v236
	v_lshlrev_b32_e32 v233, 16, v233
	v_lshlrev_b32_e32 v237, 16, v237
	v_lshlrev_b32_e32 v238, 16, v238
	v_lshlrev_b32_e32 v242, 16, v242
	v_lshlrev_b32_e32 v239, 16, v239
	v_lshlrev_b32_e32 v243, 16, v243
	v_lshlrev_b32_e32 v240, 16, v240
	v_lshlrev_b32_e32 v244, 16, v244
	v_lshlrev_b32_e32 v241, 16, v241
	v_lshlrev_b32_e32 v245, 16, v245
	s_and_b64 vcc, exec, s[42:43]
	s_cbranch_vccz .Lhz2_l1n
	v_add_u32_e32 v112, 0x0, v250
	v_cvt_f32_u32_e32 v112, v112
	v_mul_f32_e32 v112, v199, v112
	v_sin_f32_e32 v113, v112
	v_cos_f32_e32 v30, v112
	s_nop 0
	v_mul_f32_e32 v31, v113, v234
	v_mul_f32_e32 v113, v113, v230
	v_fma_f32 v230, v30, v230, v31
	v_fma_f32 v234, v30, v234, -v113
	v_add_u32_e32 v112, 0x1000, v250
	v_cvt_f32_u32_e32 v112, v112
	v_mul_f32_e32 v112, v199, v112
	v_sin_f32_e32 v113, v112
	v_cos_f32_e32 v30, v112
	s_nop 0
	v_mul_f32_e32 v31, v113, v235
	v_mul_f32_e32 v113, v113, v231
	v_fma_f32 v231, v30, v231, v31
	v_fma_f32 v235, v30, v235, -v113
	v_add_u32_e32 v112, 0x2000, v250
	v_cvt_f32_u32_e32 v112, v112
	v_mul_f32_e32 v112, v199, v112
	v_sin_f32_e32 v113, v112
	v_cos_f32_e32 v30, v112
	s_nop 0
	v_mul_f32_e32 v31, v113, v236
	v_mul_f32_e32 v113, v113, v232
	v_fma_f32 v232, v30, v232, v31
	v_fma_f32 v236, v30, v236, -v113
	v_add_u32_e32 v112, 0x3000, v250
	v_cvt_f32_u32_e32 v112, v112
	v_mul_f32_e32 v112, v199, v112
	v_sin_f32_e32 v113, v112
	v_cos_f32_e32 v30, v112
	s_nop 0
	v_mul_f32_e32 v31, v113, v237
	v_mul_f32_e32 v113, v113, v233
	v_fma_f32 v233, v30, v233, v31
	v_fma_f32 v237, v30, v237, -v113
	v_add_u32_e32 v112, 0x200, v250
	v_cvt_f32_u32_e32 v112, v112
	v_mul_f32_e32 v112, v199, v112
	v_sin_f32_e32 v113, v112
	v_cos_f32_e32 v30, v112
	s_nop 0
	v_mul_f32_e32 v31, v113, v242
	v_mul_f32_e32 v113, v113, v238
	v_fma_f32 v238, v30, v238, v31
	v_fma_f32 v242, v30, v242, -v113
	v_add_u32_e32 v112, 0x1200, v250
	v_cvt_f32_u32_e32 v112, v112
	v_mul_f32_e32 v112, v199, v112
	v_sin_f32_e32 v113, v112
	v_cos_f32_e32 v30, v112
	s_nop 0
	v_mul_f32_e32 v31, v113, v243
	v_mul_f32_e32 v113, v113, v239
	v_fma_f32 v239, v30, v239, v31
	v_fma_f32 v243, v30, v243, -v113
	v_add_u32_e32 v112, 0x2200, v250
	v_cvt_f32_u32_e32 v112, v112
	v_mul_f32_e32 v112, v199, v112
	v_sin_f32_e32 v113, v112
	v_cos_f32_e32 v30, v112
	s_nop 0
	v_mul_f32_e32 v31, v113, v244
	v_mul_f32_e32 v113, v113, v240
	v_fma_f32 v240, v30, v240, v31
	v_fma_f32 v244, v30, v244, -v113
	v_add_u32_e32 v112, 0x3200, v250
	v_cvt_f32_u32_e32 v112, v112
	v_mul_f32_e32 v112, v199, v112
	v_sin_f32_e32 v113, v112
	v_cos_f32_e32 v30, v112
	s_nop 0
	v_mul_f32_e32 v31, v113, v245
	v_mul_f32_e32 v113, v113, v241
	v_fma_f32 v241, v30, v241, v31
	v_fma_f32 v245, v30, v245, -v113
; DI float bf2f(bf16 b) { return __uint_as_float(((unsigned)b) << 16); }
; DI float cos2pi(float x) { return __builtin_amdgcn_cosf(x); }
; DI float sin2pi(float x) { return __builtin_amdgcn_sinf(x); }
; template <bool INV>
; DI void fft_lds(float2* buf_, int L, int logL, int gtid, int NTG) {
;     ...
;       for (int t = gtid; t < (L >> 2); t += NTG) {
;         const int k = t & (S - 1), base = ((t - k) << 2) | k;
;         const v2f a0 = buf[base], a1 = buf[base + S], a2 = buf[base + 2 * S], a3 = buf[base + 3 * S];
;         const float fr = (float)k * i4;
;         const v2f w1 = v2f{cos2pi(fr), sin2pi(fr)};
;         const v2f w2 = vcmul(w1, w1);
;         const v2f x0 = a0 + a2;
;         const v2f x2 = vcmulc(a0 - a2, w1);
;         const v2f x1 = a1 + a3;
;         const v2f d13 = vcmulc(a1 - a3, w1);
;         const v2f x3 = v2f{d13.y, -d13.x};
;         buf[base] = x0 + x1;
;         buf[base + S] = vcmulc(x0 - x1, w2);
;         buf[base + 2 * S] = x2 + x3;
;         buf[base + 3 * S] = vcmulc(x2 - x3, w2);
;       }
; DI void hyena_item(const Ctx& c, int ch, float* red) {
;     ...
;         for (int n = gtid; n < L; n += NTG) {
;           const float a = bf2f(zin[r0 + n]), b = bf2f(zin[r1 + n]);
;           if (p == 0) bufg[n] = make_float2(a, b);
;           else {
;             const float fr = (float)n * i2L; const float cs = cos2pi(fr), sn = sin2pi(fr);
;             bufg[n] = make_float2(a * cs + b * sn, b * cs - a * sn);
;           }
.Lhz2_l1n:
	v_sub_f32_e32 v112, v230, v232
	v_add_f32_e32 v230, v230, v232
	v_mov_b32_e32 v232, v112
	v_sub_f32_e32 v112, v234, v236
	v_add_f32_e32 v234, v234, v236
	v_mov_b32_e32 v236, v112
	v_sub_f32_e32 v112, v231, v233
	v_add_f32_e32 v231, v231, v233
	v_mov_b32_e32 v233, v112
	v_sub_f32_e32 v112, v235, v237
	v_add_f32_e32 v235, v235, v237
	v_mov_b32_e32 v237, v112
	v_mul_f32_e32 v112, v232, v106
	v_mul_f32_e32 v113, v232, v107
	v_fma_f32 v232, v236, v107, v112
	v_fma_f32 v236, v236, v106, -v113
	v_mul_f32_e32 v112, v233, v106
	v_mul_f32_e32 v113, v233, v107
	v_fma_f32 v233, v237, v107, v112
	v_fma_f32 v237, v237, v106, -v113
	v_add_f32_e32 v64, v230, v231
	v_add_f32_e32 v65, v234, v235
	v_sub_f32_e32 v230, v230, v231
	v_sub_f32_e32 v234, v234, v235
	v_mul_f32_e32 v112, v230, v108
	v_mul_f32_e32 v113, v230, v109
	v_fma_f32 v66, v234, v109, v112
	v_fma_f32 v67, v234, v108, -v113
	v_add_f32_e32 v68, v232, v237
	v_sub_f32_e32 v69, v236, v233
	v_sub_f32_e32 v231, v232, v237
	v_add_f32_e32 v235, v236, v233
	v_mul_f32_e32 v112, v231, v108
	v_mul_f32_e32 v113, v231, v109
	v_fma_f32 v70, v235, v109, v112
	v_fma_f32 v71, v235, v108, -v113
	ds_write_b64 v247, v[64:65]
	ds_write_b64 v247, v[66:67] offset:32768
	ds_write_b64 v248, v[68:69]
	ds_write_b64 v248, v[70:71] offset:32768
	v_add_u32_e32 v75, 0x200, v250
	v_cvt_f32_u32_e32 v112, v75
	v_mul_f32_e32 v112, 0x38800000, v112
	v_cos_f32_e32 v106, v112
	v_sin_f32_e32 v107, v112
	s_nop 0
	v_mul_f32_e32 v108, v107, v107
	v_mul_f32_e32 v109, v107, v106
	v_fma_f32 v108, v106, v106, -v108
	v_fma_f32 v109, v106, v107, v109
	v_sub_f32_e32 v112, v238, v240
	v_add_f32_e32 v238, v238, v240
	v_mov_b32_e32 v240, v112
	v_sub_f32_e32 v112, v242, v244
	v_add_f32_e32 v242, v242, v244
	v_mov_b32_e32 v244, v112
	v_sub_f32_e32 v112, v239, v241
	v_add_f32_e32 v239, v239, v241
	v_mov_b32_e32 v241, v112
	v_sub_f32_e32 v112, v243, v245
	v_add_f32_e32 v243, v243, v245
	v_mov_b32_e32 v245, v112
	v_mul_f32_e32 v112, v240, v106
	v_mul_f32_e32 v113, v240, v107
	v_fma_f32 v240, v244, v107, v112
	v_fma_f32 v244, v244, v106, -v113
	v_mul_f32_e32 v112, v241, v106
	v_mul_f32_e32 v113, v241, v107
	v_fma_f32 v241, v245, v107, v112
	v_fma_f32 v245, v245, v106, -v113
	v_add_f32_e32 v64, v238, v239
	v_add_f32_e32 v65, v242, v243
	v_sub_f32_e32 v238, v238, v239
	v_sub_f32_e32 v242, v242, v243
	v_mul_f32_e32 v112, v238, v108
	v_mul_f32_e32 v113, v238, v109
	v_fma_f32 v66, v242, v109, v112
	v_fma_f32 v67, v242, v108, -v113
	v_add_f32_e32 v68, v240, v245
	v_sub_f32_e32 v69, v244, v241
	v_sub_f32_e32 v239, v240, v245
	v_add_f32_e32 v243, v244, v241
	v_mul_f32_e32 v112, v239, v108
	v_mul_f32_e32 v113, v239, v109
	v_fma_f32 v70, v243, v109, v112
	v_fma_f32 v71, v243, v108, -v113
	ds_write_b64 v247, v[64:65] offset:4096
	ds_write_b64 v247, v[66:67] offset:36864
	ds_write_b64 v248, v[68:69] offset:4096
	ds_write_b64 v248, v[70:71] offset:36864
	v_add_u32_e32 v250, 0x400, v250
	v_add_u32_e32 v246, 0x800, v246
	v_add_u32_e32 v247, 0x2000, v247
	v_add_u32_e32 v248, 0x2000, v248
	s_add_i32 s100, s100, 1
	s_cmp_lg_u32 s100, 4
	s_cbranch_scc1 .Lhz2_l1
	s_branch .Lhz2_end
.Lhz2_g0:
	global_load_ushort v230, v246, s[0:1] offset:0
	global_load_ushort v234, v246, s[4:5] offset:0
	global_load_ushort v231, v246, s[0:1] offset:512
	global_load_ushort v235, v246, s[4:5] offset:512
	global_load_ushort v232, v246, s[0:1] offset:1024
	global_load_ushort v236, v246, s[4:5] offset:1024
	global_load_ushort v233, v246, s[0:1] offset:1536
	global_load_ushort v237, v246, s[4:5] offset:1536
	global_load_ushort v238, v246, s[0:1] offset:2048
	global_load_ushort v242, v246, s[4:5] offset:2048
	global_load_ushort v239, v246, s[0:1] offset:2560
	global_load_ushort v243, v246, s[4:5] offset:2560
	global_load_ushort v240, v246, s[0:1] offset:3072
	global_load_ushort v244, v246, s[4:5] offset:3072
	global_load_ushort v241, v246, s[0:1] offset:3584
	global_load_ushort v245, v246, s[4:5] offset:3584
	v_cvt_f32_u32_e32 v112, v250
	v_mul_f32_e32 v112, 0x3a800000, v112
	v_cos_f32_e32 v106, v112
	v_sin_f32_e32 v107, v112
	s_nop 0
	v_mul_f32_e32 v108, v107, v107
	v_mul_f32_e32 v109, v107, v106
	v_fma_f32 v108, v106, v106, -v108
	v_fma_f32 v109, v106, v107, v109
	v_cvt_f32_u32_e32 v74, v250
	v_mul_f32_e32 v74, 0x3a000000, v74
	s_waitcnt vmcnt(0)
	v_lshlrev_b32_e32 v230, 16, v230
	v_lshlrev_b32_e32 v234, 16, v234
	v_lshlrev_b32_e32 v231, 16, v231
	v_lshlrev_b32_e32 v235, 16, v235
	v_lshlrev_b32_e32 v232, 16, v232
	v_lshlrev_b32_e32 v236, 16, v236
	v_lshlrev_b32_e32 v233, 16, v233
	v_lshlrev_b32_e32 v237, 16, v237
	v_lshlrev_b32_e32 v238, 16, v238
	v_lshlrev_b32_e32 v242, 16, v242
	v_lshlrev_b32_e32 v239, 16, v239
	v_lshlrev_b32_e32 v243, 16, v243
	v_lshlrev_b32_e32 v240, 16, v240
	v_lshlrev_b32_e32 v244, 16, v244
	v_lshlrev_b32_e32 v241, 16, v241
	v_lshlrev_b32_e32 v245, 16, v245
	s_and_b64 vcc, exec, s[42:43]
	s_cbranch_vccz .Lhz2_g0n
; DI float bf2f(bf16 b) { return __uint_as_float(((unsigned)b) << 16); }
; DI float cos2pi(float x) { return __builtin_amdgcn_cosf(x); }
; DI float sin2pi(float x) { return __builtin_amdgcn_sinf(x); }
; template <bool INV>
; DI void fft_lds(float2* buf_, int L, int logL, int gtid, int NTG) {
;     ...
;     if (logL & 1) {
;       const float is2 = 0.5f / (float)s;
; #pragma unroll 4
;       for (int t = gtid; t < (L >> 1); t += NTG) {
;         const int k = t & (s - 1), i = ((t - k) << 1) | k, j = i + s;
;         const v2f a = buf[i], b = buf[j];
;         const float fr = (float)k * is2;
;         const v2f w = v2f{cos2pi(fr), sin2pi(fr)};
;         buf[i] = a + b;
;         buf[j] = vcmulc(a - b, w);
;       }
;       __syncthreads();
;       s >>= 1;
;     }
;     for (; s >= 2; s >>= 2) {
;       const int S = s >> 1;
;       const float i4 = 0.25f / (float)S;
; #pragma unroll 8
;       for (int t = gtid; t < (L >> 2); t += NTG) {
;         const int k = t & (S - 1), base = ((t - k) << 2) | k;
;         const v2f a0 = buf[base], a1 = buf[base + S], a2 = buf[base + 2 * S], a3 = buf[base + 3 * S];
;         const float fr = (float)k * i4;
;         const v2f w1 = v2f{cos2pi(fr), sin2pi(fr)};
;         const v2f w2 = vcmul(w1, w1);
;         const v2f x0 = a0 + a2;
;         const v2f x2 = vcmulc(a0 - a2, w1);
;         const v2f x1 = a1 + a3;
;         const v2f d13 = vcmulc(a1 - a3, w1);
;         const v2f x3 = v2f{d13.y, -d13.x};
;         buf[base] = x0 + x1;
;         buf[base + S] = vcmulc(x0 - x1, w2);
;         buf[base + 2 * S] = x2 + x3;
;         buf[base + 3 * S] = vcmulc(x2 - x3, w2);
;       }
; DI void hyena_item(const Ctx& c, int ch, float* red) {
;     ...
;         for (int n = gtid; n < L; n += NTG) {
;           const float a = bf2f(zin[r0 + n]), b = bf2f(zin[r1 + n]);
;           if (p == 0) bufg[n] = make_float2(a, b);
;           else {
;             const float fr = (float)n * i2L; const float cs = cos2pi(fr), sn = sin2pi(fr);
;             bufg[n] = make_float2(a * cs + b * sn, b * cs - a * sn);
;           }
	v_add_u32_e32 v112, 0x0, v250
	v_cvt_f32_u32_e32 v112, v112
	v_mul_f32_e32 v112, v199, v112
	v_sin_f32_e32 v113, v112
	v_cos_f32_e32 v30, v112
	s_nop 0
	v_mul_f32_e32 v31, v113, v234
	v_mul_f32_e32 v113, v113, v230
	v_fma_f32 v230, v30, v230, v31
	v_fma_f32 v234, v30, v234, -v113
	v_add_u32_e32 v112, 0x100, v250
	v_cvt_f32_u32_e32 v112, v112
	v_mul_f32_e32 v112, v199, v112
	v_sin_f32_e32 v113, v112
	v_cos_f32_e32 v30, v112
	s_nop 0
	v_mul_f32_e32 v31, v113, v235
	v_mul_f32_e32 v113, v113, v231
	v_fma_f32 v231, v30, v231, v31
	v_fma_f32 v235, v30, v235, -v113
	v_add_u32_e32 v112, 0x200, v250
	v_cvt_f32_u32_e32 v112, v112
	v_mul_f32_e32 v112, v199, v112
	v_sin_f32_e32 v113, v112
	v_cos_f32_e32 v30, v112
	s_nop 0
	v_mul_f32_e32 v31, v113, v236
	v_mul_f32_e32 v113, v113, v232
	v_fma_f32 v232, v30, v232, v31
	v_fma_f32 v236, v30, v236, -v113
	v_add_u32_e32 v112, 0x300, v250
	v_cvt_f32_u32_e32 v112, v112
	v_mul_f32_e32 v112, v199, v112
	v_sin_f32_e32 v113, v112
	v_cos_f32_e32 v30, v112
	s_nop 0
	v_mul_f32_e32 v31, v113, v237
	v_mul_f32_e32 v113, v113, v233
	v_fma_f32 v233, v30, v233, v31
	v_fma_f32 v237, v30, v237, -v113
	v_add_u32_e32 v112, 0x400, v250
	v_cvt_f32_u32_e32 v112, v112
	v_mul_f32_e32 v112, v199, v112
	v_sin_f32_e32 v113, v112
	v_cos_f32_e32 v30, v112
	s_nop 0
	v_mul_f32_e32 v31, v113, v242
	v_mul_f32_e32 v113, v113, v238
	v_fma_f32 v238, v30, v238, v31
	v_fma_f32 v242, v30, v242, -v113
	v_add_u32_e32 v112, 0x500, v250
	v_cvt_f32_u32_e32 v112, v112
	v_mul_f32_e32 v112, v199, v112
	v_sin_f32_e32 v113, v112
	v_cos_f32_e32 v30, v112
	s_nop 0
	v_mul_f32_e32 v31, v113, v243
	v_mul_f32_e32 v113, v113, v239
	v_fma_f32 v239, v30, v239, v31
	v_fma_f32 v243, v30, v243, -v113
	v_add_u32_e32 v112, 0x600, v250
	v_cvt_f32_u32_e32 v112, v112
	v_mul_f32_e32 v112, v199, v112
	v_sin_f32_e32 v113, v112
	v_cos_f32_e32 v30, v112
	s_nop 0
	v_mul_f32_e32 v31, v113, v244
	v_mul_f32_e32 v113, v113, v240
	v_fma_f32 v240, v30, v240, v31
	v_fma_f32 v244, v30, v244, -v113
	v_add_u32_e32 v112, 0x700, v250
	v_cvt_f32_u32_e32 v112, v112
	v_mul_f32_e32 v112, v199, v112
	v_sin_f32_e32 v113, v112
	v_cos_f32_e32 v30, v112
	s_nop 0
	v_mul_f32_e32 v31, v113, v245
	v_mul_f32_e32 v113, v113, v241
	v_fma_f32 v241, v30, v241, v31
	v_fma_f32 v245, v30, v245, -v113
.Lhz2_g0n:
	v_cos_f32_e32 v110, v74
	v_sin_f32_e32 v111, v74
	v_sub_f32_e32 v112, v230, v238
	v_add_f32_e32 v230, v230, v238
	v_mov_b32_e32 v238, v112
	v_sub_f32_e32 v112, v234, v242
	v_add_f32_e32 v234, v234, v242
	v_mov_b32_e32 v242, v112
	v_mul_f32_e32 v112, v238, v110
	v_mul_f32_e32 v113, v238, v111
	v_fma_f32 v238, v242, v111, v112
	v_fma_f32 v242, v242, v110, -v113
	v_add_f32_e32 v73, 0x3e000000, v74
	v_cos_f32_e32 v110, v73
	v_sin_f32_e32 v111, v73
	v_sub_f32_e32 v112, v231, v239
	v_add_f32_e32 v231, v231, v239
	v_mov_b32_e32 v239, v112
	v_sub_f32_e32 v112, v235, v243
	v_add_f32_e32 v235, v235, v243
	v_mov_b32_e32 v243, v112
	v_mul_f32_e32 v112, v239, v110
	v_mul_f32_e32 v113, v239, v111
	v_fma_f32 v239, v243, v111, v112
	v_fma_f32 v243, v243, v110, -v113
	v_add_f32_e32 v73, 0.25, v74
	v_cos_f32_e32 v110, v73
	v_sin_f32_e32 v111, v73
	v_sub_f32_e32 v112, v232, v240
	v_add_f32_e32 v232, v232, v240
	v_mov_b32_e32 v240, v112
	v_sub_f32_e32 v112, v236, v244
	v_add_f32_e32 v236, v236, v244
	v_mov_b32_e32 v244, v112
	v_mul_f32_e32 v112, v240, v110
	v_mul_f32_e32 v113, v240, v111
	v_fma_f32 v240, v244, v111, v112
	v_fma_f32 v244, v244, v110, -v113
	v_add_f32_e32 v73, 0x3ec00000, v74
	v_cos_f32_e32 v110, v73
	v_sin_f32_e32 v111, v73
	v_sub_f32_e32 v112, v233, v241
	v_add_f32_e32 v233, v233, v241
	v_mov_b32_e32 v241, v112
	v_sub_f32_e32 v112, v237, v245
	v_add_f32_e32 v237, v237, v245
	v_mov_b32_e32 v245, v112
	v_mul_f32_e32 v112, v241, v110
	v_mul_f32_e32 v113, v241, v111
	v_fma_f32 v241, v245, v111, v112
	v_fma_f32 v245, v245, v110, -v113
	v_sub_f32_e32 v112, v230, v232
	v_add_f32_e32 v230, v230, v232
	v_mov_b32_e32 v232, v112
	v_sub_f32_e32 v112, v234, v236
	v_add_f32_e32 v234, v234, v236
	v_mov_b32_e32 v236, v112
	v_sub_f32_e32 v112, v231, v233
	v_add_f32_e32 v231, v231, v233
	v_mov_b32_e32 v233, v112
	v_sub_f32_e32 v112, v235, v237
	v_add_f32_e32 v235, v235, v237
	v_mov_b32_e32 v237, v112
	v_mul_f32_e32 v112, v232, v106
	v_mul_f32_e32 v113, v232, v107
	v_fma_f32 v232, v236, v107, v112
	v_fma_f32 v236, v236, v106, -v113
	v_mul_f32_e32 v112, v233, v106
	v_mul_f32_e32 v113, v233, v107
	v_fma_f32 v233, v237, v107, v112
	v_fma_f32 v237, v237, v106, -v113
	v_add_f32_e32 v64, v230, v231
	v_add_f32_e32 v65, v234, v235
	v_sub_f32_e32 v230, v230, v231
	v_sub_f32_e32 v234, v234, v235
	v_mul_f32_e32 v112, v230, v108
	v_mul_f32_e32 v113, v230, v109
	v_fma_f32 v66, v234, v109, v112
	v_fma_f32 v67, v234, v108, -v113
	v_add_f32_e32 v68, v232, v237
	v_sub_f32_e32 v69, v236, v233
	v_sub_f32_e32 v231, v232, v237
	v_add_f32_e32 v235, v236, v233
	v_mul_f32_e32 v112, v231, v108
	v_mul_f32_e32 v113, v231, v109
	v_fma_f32 v70, v235, v109, v112
	v_fma_f32 v71, v235, v108, -v113
	ds_write_b64 v247, v[64:65]
	ds_write_b64 v247, v[66:67] offset:2048
	ds_write_b64 v247, v[68:69] offset:4096
	ds_write_b64 v247, v[70:71] offset:6144
	v_sub_f32_e32 v112, v238, v240
	v_add_f32_e32 v238, v238, v240
	v_mov_b32_e32 v240, v112
	v_sub_f32_e32 v112, v242, v244
	v_add_f32_e32 v242, v242, v244
	v_mov_b32_e32 v244, v112
	v_sub_f32_e32 v112, v239, v241
	v_add_f32_e32 v239, v239, v241
	v_mov_b32_e32 v241, v112
	v_sub_f32_e32 v112, v243, v245
	v_add_f32_e32 v243, v243, v245
	v_mov_b32_e32 v245, v112
	v_mul_f32_e32 v112, v240, v106
	v_mul_f32_e32 v113, v240, v107
	v_fma_f32 v240, v244, v107, v112
	v_fma_f32 v244, v244, v106, -v113
	v_mul_f32_e32 v112, v241, v106
	v_mul_f32_e32 v113, v241, v107
	v_fma_f32 v241, v245, v107, v112
	v_fma_f32 v245, v245, v106, -v113
	v_add_f32_e32 v64, v238, v239
	v_add_f32_e32 v65, v242, v243
	v_sub_f32_e32 v238, v238, v239
	v_sub_f32_e32 v242, v242, v243
	v_mul_f32_e32 v112, v238, v108
	v_mul_f32_e32 v113, v238, v109
	v_fma_f32 v66, v242, v109, v112
	v_fma_f32 v67, v242, v108, -v113
	v_add_f32_e32 v68, v240, v245
	v_sub_f32_e32 v69, v244, v241
	v_sub_f32_e32 v239, v240, v245
	v_add_f32_e32 v243, v244, v241
	v_mul_f32_e32 v112, v239, v108
	v_mul_f32_e32 v113, v239, v109
	v_fma_f32 v70, v243, v109, v112
	v_fma_f32 v71, v243, v108, -v113
	ds_write_b64 v247, v[64:65] offset:8192
	ds_write_b64 v247, v[66:67] offset:10240
	ds_write_b64 v247, v[68:69] offset:12288
	ds_write_b64 v247, v[70:71] offset:14336
	v_add_u32_e32 v250, 64, v250
	v_add_u32_e32 v246, 0x80, v246
	v_add_u32_e32 v247, 0x200, v247
	s_add_i32 s100, s100, 1
	s_cmp_lg_u32 s100, 4
	s_cbranch_scc1 .Lhz2_g0

; DI void hyena_item(const Ctx& c, int ch, float* red) {
;     ...
;         __syncthreads();
;         fft_lds<false>(bufg, L, logL, gtid, NTG);
.LBB0_694:
	s_or_b64 exec, exec, s[0:1]
	s_and_b64 vcc, exec, s[52:53]
	s_movk_i32 s6, 0x800
	s_cmp_eq_u32 s61, 64
	s_cselect_b32 s6, 0x80, s6
	s_waitcnt lgkmcnt(0)
	s_barrier
	s_branch .LBB0_705
	s_and_saveexec_b64 s[0:1], s[16:17]
	s_cbranch_execz .LBB0_703
	v_mov_b32_e32 v30, v38
	s_and_saveexec_b64 s[4:5], s[44:45]
	s_cbranch_execz .LBB0_700
	s_mov_b64 s[54:55], 0
	v_mov_b32_e32 v31, v88
	v_mov_b32_e32 v32, v100
	v_mov_b32_e32 v30, v38

; DI float cos2pi(float x) { return __builtin_amdgcn_cosf(x); }
; DI float sin2pi(float x) { return __builtin_amdgcn_sinf(x); }
; template <bool INV>
; DI void fft_lds(float2* buf_, int L, int logL, int gtid, int NTG) {
;     ...
;       for (int t = gtid; t < (L >> 2); t += NTG) {
;         const int k = t & (S - 1), base = ((t - k) << 2) | k;
;         const v2f a0 = buf[base], a1 = buf[base + S], a2 = buf[base + 2 * S], a3 = buf[base + 3 * S];
;         const float fr = (float)k * i4;
;         const v2f w1 = v2f{cos2pi(fr), sin2pi(fr)};
;         const v2f w2 = vcmul(w1, w1);
;         const v2f x0 = a0 + a2;
;         const v2f x2 = vcmulc(a0 - a2, w1);
;         const v2f x1 = a1 + a3;
;         const v2f d13 = vcmulc(a1 - a3, w1);
;         const v2f x3 = v2f{d13.y, -d13.x};
;         buf[base] = x0 + x1;
;         buf[base + S] = vcmulc(x0 - x1, w2);
;         buf[base + 2 * S] = x2 + x3;
;         buf[base + 3 * S] = vcmulc(x2 - x3, w2);
;       }
;       __syncthreads();
;     }
.Lffl_fb_64:
	ds_read_b64 v[230:231], v72 offset:2048
	ds_read_b64 v[232:233], v73 offset:2048
	ds_read_b64 v[234:235], v74 offset:2048
	ds_read_b64 v[236:237], v75 offset:2048
	s_waitcnt lgkmcnt(8)
	v_add_f32_e32 v110, v64, v68
	v_sub_f32_e32 v112, v64, v68
	v_add_f32_e32 v30, v66, v70
	v_sub_f32_e32 v32, v66, v70
	v_add_f32_e32 v111, v65, v69
	v_sub_f32_e32 v113, v65, v69
	v_add_f32_e32 v31, v67, v71
	v_sub_f32_e32 v33, v67, v71
	v_mul_f32_e32 v251, v112, v106
	v_mul_f32_e32 v252, v112, v107
	v_fma_f32 v47, v113, v107, v251
	v_fma_f32 v250, v113, v106, -v252
	v_mul_f32_e32 v251, v32, v106
	v_mul_f32_e32 v252, v32, v107
	v_fma_f32 v253, v33, v107, v251
	v_fma_f32 v254, v33, v106, -v252
	v_add_f32_e32 v64, v110, v30
	v_add_f32_e32 v65, v111, v31
	v_sub_f32_e32 v110, v110, v30
	v_sub_f32_e32 v111, v111, v31
	v_mul_f32_e32 v251, v110, v108
	v_mul_f32_e32 v252, v110, v109
	v_fma_f32 v66, v111, v109, v251
	v_fma_f32 v67, v111, v108, -v252
	v_add_f32_e32 v68, v47, v254
	v_sub_f32_e32 v69, v250, v253
	v_sub_f32_e32 v30, v47, v254
	v_add_f32_e32 v31, v250, v253
	v_mul_f32_e32 v251, v30, v108
	v_mul_f32_e32 v252, v30, v109
	v_fma_f32 v70, v31, v109, v251
	v_fma_f32 v71, v31, v108, -v252
	ds_write_b64 v72, v[64:65]
	ds_write_b64 v73, v[66:67]
	ds_write_b64 v74, v[68:69]
	ds_write_b64 v75, v[70:71]
	ds_read_b64 v[64:65], v72 offset:4096
	ds_read_b64 v[66:67], v73 offset:4096
	ds_read_b64 v[68:69], v74 offset:4096
	ds_read_b64 v[70:71], v75 offset:4096
	s_waitcnt lgkmcnt(8)
	v_add_f32_e32 v110, v230, v234
	v_sub_f32_e32 v112, v230, v234
	v_add_f32_e32 v30, v232, v236
	v_sub_f32_e32 v32, v232, v236
	v_add_f32_e32 v111, v231, v235
	v_sub_f32_e32 v113, v231, v235
	v_add_f32_e32 v31, v233, v237
	v_sub_f32_e32 v33, v233, v237
	v_mul_f32_e32 v251, v112, v106
	v_mul_f32_e32 v252, v112, v107
	v_fma_f32 v47, v113, v107, v251
	v_fma_f32 v250, v113, v106, -v252
	v_mul_f32_e32 v251, v32, v106
	v_mul_f32_e32 v252, v32, v107
	v_fma_f32 v253, v33, v107, v251
	v_fma_f32 v254, v33, v106, -v252
	v_add_f32_e32 v230, v110, v30
	v_add_f32_e32 v231, v111, v31
	v_sub_f32_e32 v110, v110, v30
	v_sub_f32_e32 v111, v111, v31
	v_mul_f32_e32 v251, v110, v108
	v_mul_f32_e32 v252, v110, v109
	v_fma_f32 v232, v111, v109, v251
	v_fma_f32 v233, v111, v108, -v252
	v_add_f32_e32 v234, v47, v254
	v_sub_f32_e32 v235, v250, v253
	v_sub_f32_e32 v30, v47, v254
	v_add_f32_e32 v31, v250, v253
	v_mul_f32_e32 v251, v30, v108
	v_mul_f32_e32 v252, v30, v109
	v_fma_f32 v236, v31, v109, v251
	v_fma_f32 v237, v31, v108, -v252
	ds_write_b64 v72, v[230:231] offset:2048
	ds_write_b64 v73, v[232:233] offset:2048
	ds_write_b64 v74, v[234:235] offset:2048
	ds_write_b64 v75, v[236:237] offset:2048
	v_add_u32_e32 v72, 0x1000, v72
	v_add_u32_e32 v73, 0x1000, v73
	v_add_u32_e32 v74, 0x1000, v74
	v_add_u32_e32 v75, 0x1000, v75
	s_add_i32 s5, s5, -1
	s_cmp_lg_u32 s5, 0
	s_cbranch_scc1 .Lffl_fb_64
	s_branch .Lffs_f_nb
	s_branch .Lffs_f_skip
.Lffs_f_nb:
	s_or_b64 exec, exec, s[54:55]
	s_lshr_b32 s6, s6, 2
	s_waitcnt lgkmcnt(0)
	s_branch .LBB0_705
.Lffs_f_fz:
	s_or_b64 exec, exec, s[54:55]
	s_mov_b32 s6, 1
	s_mov_b32 s7, 4
	s_waitcnt lgkmcnt(0)
	s_branch .LBB0_723

; DI float cos2pi(float x) { return __builtin_amdgcn_cosf(x); }
; DI float sin2pi(float x) { return __builtin_amdgcn_sinf(x); }
; template <bool INV>
; DI void fft_lds(float2* buf_, int L, int logL, int gtid, int NTG) {
;     ...
;     for (int f = 0; f < nf; ++f, S <<= 2) {
;       const float i4 = 0.25f / (float)S;
; #pragma unroll 8
;       for (int t = gtid; t < (L >> 2); t += NTG) {
;         const int k = t & (S - 1), base = ((t - k) << 2) | k;
;         const v2f p0 = buf[base], p1 = buf[base + S], p2 = buf[base + 2 * S], p3 = buf[base + 3 * S];
;         const float fr = (float)k * i4;
;         const v2f w1 = v2f{cos2pi(fr), sin2pi(fr)};
;         const v2f w2 = vcmul(w1, w1);
;         const v2f b1 = vcmul(p1, w2), b3 = vcmul(p3, w2);
;         const v2f q0 = p0 + b1, q1 = p0 - b1, q2 = p2 + b3, q3 = p2 - b3;
;         const v2f c2 = vcmul(q2, w1);
;         const v2f t3 = vcmul(q3, w1); const v2f c3 = v2f{-t3.y, t3.x};
;         buf[base] = q0 + c2;
;         buf[base + 2 * S] = q0 - c2;
;         buf[base + S] = q1 + c3;
;         buf[base + 3 * S] = q1 - c3;
;       }
;       __syncthreads();
.Lffl_ib_64:
	ds_read_b64 v[230:231], v72 offset:2048
	ds_read_b64 v[232:233], v73 offset:2048
	ds_read_b64 v[234:235], v74 offset:2048
	ds_read_b64 v[236:237], v75 offset:2048
	s_waitcnt lgkmcnt(8)
	v_mul_f32_e32 v251, v67, v109
	v_mul_f32_e32 v252, v67, v108
	v_fma_f32 v110, v66, v108, -v251
	v_fma_f32 v111, v66, v109, v252
	v_mul_f32_e32 v251, v71, v109
	v_mul_f32_e32 v252, v71, v108
	v_fma_f32 v112, v70, v108, -v251
	v_fma_f32 v113, v70, v109, v252
	v_add_f32_e32 v30, v64, v110
	v_sub_f32_e32 v32, v64, v110
	v_add_f32_e32 v47, v68, v112
	v_sub_f32_e32 v253, v68, v112
	v_add_f32_e32 v31, v65, v111
	v_sub_f32_e32 v33, v65, v111
	v_add_f32_e32 v250, v69, v113
	v_sub_f32_e32 v254, v69, v113
	v_mul_f32_e32 v251, v250, v107
	v_mul_f32_e32 v252, v250, v106
	v_fma_f32 v110, v47, v106, -v251
	v_fma_f32 v111, v47, v107, v252
	v_mul_f32_e32 v251, v254, v107
	v_mul_f32_e32 v252, v254, v106
	v_fma_f32 v112, v253, v106, -v251
	v_fma_f32 v113, v253, v107, v252
	v_add_f32_e32 v64, v30, v110
	v_add_f32_e32 v65, v31, v111
	v_sub_f32_e32 v66, v32, v113
	v_add_f32_e32 v67, v33, v112
	v_sub_f32_e32 v68, v30, v110
	v_sub_f32_e32 v69, v31, v111
	v_add_f32_e32 v70, v32, v113
	v_sub_f32_e32 v71, v33, v112
	ds_write_b64 v72, v[64:65]
	ds_write_b64 v73, v[66:67]
	ds_write_b64 v74, v[68:69]
	ds_write_b64 v75, v[70:71]
	ds_read_b64 v[64:65], v72 offset:4096
	ds_read_b64 v[66:67], v73 offset:4096
	ds_read_b64 v[68:69], v74 offset:4096
	ds_read_b64 v[70:71], v75 offset:4096
	s_waitcnt lgkmcnt(8)
	v_mul_f32_e32 v251, v233, v109
	v_mul_f32_e32 v252, v233, v108
	v_fma_f32 v110, v232, v108, -v251
	v_fma_f32 v111, v232, v109, v252
	v_mul_f32_e32 v251, v237, v109
	v_mul_f32_e32 v252, v237, v108
	v_fma_f32 v112, v236, v108, -v251
	v_fma_f32 v113, v236, v109, v252
	v_add_f32_e32 v30, v230, v110
	v_sub_f32_e32 v32, v230, v110
	v_add_f32_e32 v47, v234, v112
	v_sub_f32_e32 v253, v234, v112
	v_add_f32_e32 v31, v231, v111
	v_sub_f32_e32 v33, v231, v111
	v_add_f32_e32 v250, v235, v113
	v_sub_f32_e32 v254, v235, v113
	v_mul_f32_e32 v251, v250, v107
	v_mul_f32_e32 v252, v250, v106
	v_fma_f32 v110, v47, v106, -v251
	v_fma_f32 v111, v47, v107, v252
	v_mul_f32_e32 v251, v254, v107
	v_mul_f32_e32 v252, v254, v106
	v_fma_f32 v112, v253, v106, -v251
	v_fma_f32 v113, v253, v107, v252
	v_add_f32_e32 v230, v30, v110
	v_add_f32_e32 v231, v31, v111
	v_sub_f32_e32 v232, v32, v113
	v_add_f32_e32 v233, v33, v112
	v_sub_f32_e32 v234, v30, v110
	v_sub_f32_e32 v235, v31, v111
	v_add_f32_e32 v236, v32, v113
	v_sub_f32_e32 v237, v33, v112
	ds_write_b64 v72, v[230:231] offset:2048
	ds_write_b64 v73, v[232:233] offset:2048
	ds_write_b64 v74, v[234:235] offset:2048
	ds_write_b64 v75, v[236:237] offset:2048
	v_add_u32_e32 v72, 0x1000, v72
	v_add_u32_e32 v73, 0x1000, v73
	v_add_u32_e32 v74, 0x1000, v74
	v_add_u32_e32 v75, 0x1000, v75
	s_add_i32 s5, s5, -1
	s_cmp_lg_u32 s5, 0
	s_cbranch_scc1 .Lffl_ib_64
	s_branch .LBB0_722
	s_branch .Lffs_i_skip
.Lffs_i_nb:
	s_or_b64 exec, exec, s[54:55]
	s_add_i32 s6, s6, 1
	s_lshl_b32 s7, s7, 2
	s_waitcnt lgkmcnt(0)
	s_branch .LBB0_723
